# first grid seam uses XCD barrier instead of cg sync; layer-0 out-proj tiles of the 32 SSM-table blocks moved to idle blocks
# speedup vs baseline: 1.0093x; 1.0093x over previous
.LBB0_166:
	s_andn2_b64 vcc, exec, s[0:1]
	s_cbranch_vccnz .LBB0_322
	v_readlane_b32 s0, v255, 22
	s_cmpk_gt_i32 s0, 0x17f
	v_readlane_b32 s1, v255, 23
	s_cbranch_scc1 .LBB0_176
	s_mov_b32 s32, 0
	s_cmp_eq_u64 s[48:49], 0
	s_cbranch_scc1 .Lrb_none
	s_cmpk_lg_i32 s89, 0x100
	s_cbranch_scc1 .Lrb_none
	s_cmpk_lt_i32 s0, 0x80
	s_cbranch_scc1 .Lrb_none
	s_cmpk_lt_i32 s0, 0xa0
	s_cbranch_scc1 .LBB0_176
	s_cmpk_lt_i32 s0, 0xc0
	s_cbranch_scc0 .Lrb_none
	s_mov_b32 s32, 1
.Lrb_none:
	v_readlane_b32 s0, v255, 22
	s_lshl_b32 s5, s0, 6
	s_lshl_b32 s6, s89, 6
	s_mov_b32 s7, s0
	v_readlane_b32 s1, v255, 23
	s_branch .LBB0_170
.LBB0_169:
	v_lshrrev_b32_e32 v0, 2, v140
	v_and_b32_e32 v0, 0x3fffc0, v0
	v_and_or_b32 v130, v140, 15, s0
	v_add_lshl_u32 v0, v130, v0, 10
	v_lshrrev_b32_e32 v130, 1, v140
	s_lshl_b32 s0, s10, 8
	v_and_b32_e32 v130, 0x78, v130
	v_or3_b32 v130, v0, s0, v130
	s_barrier
	v_readlane_b32 s0, v255, 30
	v_cvt_pk_bf16_f32 v62, v62, v63
	v_cvt_pk_bf16_f32 v63, v64, v65
	v_cvt_pk_bf16_f32 v64, v58, v59
	v_add_u32_e32 v58, 0x20080, v130
	v_ashrrev_i32_e32 v131, 31, v130
	v_readlane_b32 s1, v255, 31
	v_cvt_pk_bf16_f32 v110, v110, v111
	v_cvt_pk_bf16_f32 v111, v112, v113
	v_cvt_pk_bf16_f32 v112, v106, v107
	v_add_u32_e32 v106, 0x4000, v130
	v_ashrrev_i32_e32 v59, 31, v58
	v_cvt_pk_bf16_f32 v46, v46, v47
	v_cvt_pk_bf16_f32 v47, v48, v49
	v_cvt_pk_bf16_f32 v48, v42, v43
	v_add_u32_e32 v42, 0x24000, v130
	v_lshl_add_u64 v[132:133], v[130:131], 1, s[0:1]
	v_cvt_pk_bf16_f32 v113, v108, v109
	v_ashrrev_i32_e32 v107, 31, v106
	v_lshl_add_u64 v[58:59], v[58:59], 1, s[0:1]
	v_cvt_pk_bf16_f32 v49, v44, v45
	v_ashrrev_i32_e32 v43, 31, v42
	global_store_dwordx4 v[132:133], v[110:113], off offset:256
	v_cvt_pk_bf16_f32 v108, v114, v115
	v_cvt_pk_bf16_f32 v109, v116, v117
	v_lshl_add_u64 v[110:111], v[106:107], 1, s[0:1]
	v_cvt_pk_bf16_f32 v106, v118, v119
	v_cvt_pk_bf16_f32 v107, v120, v121
	global_store_dwordx4 v[58:59], v[46:49], off
	v_cvt_pk_bf16_f32 v44, v50, v51
	v_cvt_pk_bf16_f32 v45, v52, v53
	v_lshl_add_u64 v[46:47], v[42:43], 1, s[0:1]
	v_cvt_pk_bf16_f32 v42, v54, v55
	v_cvt_pk_bf16_f32 v43, v56, v57
	global_store_dwordx4 v[110:111], v[106:109], off
	global_store_dwordx4 v[46:47], v[42:45], off
	v_cvt_pk_bf16_f32 v94, v94, v95
	v_add_u32_e32 v106, 0x4080, v130
	v_add_u32_e32 v42, 0x24080, v130
	v_ashrrev_i32_e32 v107, 31, v106
	v_cvt_pk_bf16_f32 v95, v96, v97
	v_cvt_pk_bf16_f32 v96, v90, v91
	v_add_u32_e32 v90, 0x8000, v130
	v_ashrrev_i32_e32 v43, 31, v42
	v_cvt_pk_bf16_f32 v30, v30, v31
	v_cvt_pk_bf16_f32 v31, v32, v33
	v_cvt_pk_bf16_f32 v32, v26, v27
	v_add_u32_e32 v26, 0x28000, v130
	v_lshl_add_u64 v[106:107], v[106:107], 1, s[0:1]
	v_cvt_pk_bf16_f32 v97, v92, v93
	v_ashrrev_i32_e32 v91, 31, v90
	v_lshl_add_u64 v[42:43], v[42:43], 1, s[0:1]
	v_cvt_pk_bf16_f32 v33, v28, v29
	v_ashrrev_i32_e32 v27, 31, v26
	global_store_dwordx4 v[106:107], v[94:97], off
	v_cvt_pk_bf16_f32 v92, v98, v99
	v_cvt_pk_bf16_f32 v93, v100, v101
	v_lshl_add_u64 v[94:95], v[90:91], 1, s[0:1]
	v_cvt_pk_bf16_f32 v90, v102, v103
	v_cvt_pk_bf16_f32 v91, v104, v105
	global_store_dwordx4 v[42:43], v[30:33], off
	v_cvt_pk_bf16_f32 v28, v34, v35
	v_cvt_pk_bf16_f32 v29, v36, v37
	v_lshl_add_u64 v[30:31], v[26:27], 1, s[0:1]
	v_cvt_pk_bf16_f32 v26, v38, v39
	v_cvt_pk_bf16_f32 v27, v40, v41
	global_store_dwordx4 v[94:95], v[90:93], off
	global_store_dwordx4 v[30:31], v[26:29], off
	v_cvt_pk_bf16_f32 v78, v78, v79
	v_add_u32_e32 v90, 0x8080, v130
	v_add_u32_e32 v26, 0x28080, v130
	v_ashrrev_i32_e32 v91, 31, v90
	v_cvt_pk_bf16_f32 v79, v80, v81
	v_cvt_pk_bf16_f32 v80, v74, v75
	v_add_u32_e32 v74, 0xc000, v130
	v_ashrrev_i32_e32 v27, 31, v26
	v_cvt_pk_bf16_f32 v14, v14, v15
	v_cvt_pk_bf16_f32 v15, v16, v17
	v_cvt_pk_bf16_f32 v16, v10, v11
	v_add_u32_e32 v10, 0x2c000, v130
	v_lshl_add_u64 v[90:91], v[90:91], 1, s[0:1]
	v_cvt_pk_bf16_f32 v81, v76, v77
	v_ashrrev_i32_e32 v75, 31, v74
	v_lshl_add_u64 v[26:27], v[26:27], 1, s[0:1]
	v_cvt_pk_bf16_f32 v17, v12, v13
	v_ashrrev_i32_e32 v11, 31, v10
	global_store_dwordx4 v[90:91], v[78:81], off
	v_cvt_pk_bf16_f32 v76, v82, v83
	v_cvt_pk_bf16_f32 v77, v84, v85
	v_lshl_add_u64 v[78:79], v[74:75], 1, s[0:1]
	v_cvt_pk_bf16_f32 v74, v86, v87
	v_cvt_pk_bf16_f32 v75, v88, v89
	global_store_dwordx4 v[26:27], v[14:17], off
	v_cvt_pk_bf16_f32 v12, v18, v19
	v_cvt_pk_bf16_f32 v13, v20, v21
	v_lshl_add_u64 v[14:15], v[10:11], 1, s[0:1]
	v_cvt_pk_bf16_f32 v10, v22, v23
	v_cvt_pk_bf16_f32 v11, v24, v25
	global_store_dwordx4 v[78:79], v[74:77], off
	v_cvt_pk_bf16_f32 v70, v70, v71
	v_cvt_pk_bf16_f32 v71, v72, v73
	v_add_u32_e32 v74, 0xc080, v130
	v_cvt_pk_bf16_f32 v72, v66, v67
	v_add_u32_e32 v66, 0x20000, v130
	global_store_dwordx4 v[14:15], v[10:13], off
	v_ashrrev_i32_e32 v75, 31, v74
	v_ashrrev_i32_e32 v67, 31, v66
	v_add_u32_e32 v10, 0x2c080, v130
	v_ashrrev_i32_e32 v11, 31, v10
	s_add_i32 s7, s7, s89
	s_add_i32 s5, s5, s6
	s_cmp_eq_u32 s32, 1
	s_cbranch_scc0 .Lrb_keep
	s_mov_b32 s32, 0
	s_sub_i32 s7, s7, 0x120
	s_lshl_b32 s5, s7, 6
.Lrb_keep:
	v_cvt_pk_bf16_f32 v126, v126, v127
	v_cvt_pk_bf16_f32 v127, v128, v129
	v_cvt_pk_bf16_f32 v128, v122, v123
	v_cvt_pk_bf16_f32 v129, v124, v125
	v_lshl_add_u64 v[74:75], v[74:75], 1, s[0:1]
	v_cvt_pk_bf16_f32 v73, v68, v69
	v_lshl_add_u64 v[66:67], v[66:67], 1, s[0:1]
	v_cvt_pk_bf16_f32 v65, v60, v61
	v_lshl_add_u64 v[10:11], v[10:11], 1, s[0:1]
	v_cvt_pk_bf16_f32 v6, v6, v7
	v_cvt_pk_bf16_f32 v7, v8, v9
	v_cvt_pk_bf16_f32 v8, v2, v3
	v_cvt_pk_bf16_f32 v9, v4, v5
	s_cmpk_lt_i32 s7, 0x180
	global_store_dwordx4 v[132:133], v[126:129], off
	global_store_dwordx4 v[74:75], v[70:73], off
	global_store_dwordx4 v[66:67], v[62:65], off
	global_store_dwordx4 v[10:11], v[6:9], off
	s_cbranch_scc0 .LBB0_176

.LBB0_1915:
	v_readlane_b32 s0, v253, 2
	v_readlane_b32 s1, v253, 3
	s_cmp_lg_u32 s2, s0
	s_mov_b64 s[0:1], -1
	s_waitcnt vmcnt(0)
	s_waitcnt vmcnt(0)
	s_barrier
	s_mov_b64 s[0:1], exec
	v_readlane_b32 s2, v253, 0
	v_readlane_b32 s3, v253, 1
	s_and_b64 s[2:3], s[0:1], s[2:3]
	s_mov_b64 exec, s[2:3]
	s_cbranch_execz .LBB0_1968
	v_readlane_b32 s2, v254, 36
	s_waitcnt vmcnt(0) expcnt(0) lgkmcnt(0)
	s_nop 0
	v_mov_b32_e32 v0, s2
	ds_read_b32 v3, v0
	v_readlane_b32 s2, v254, 37
	s_waitcnt lgkmcnt(0)
	v_cmp_ne_u32_e32 vcc, 0, v3
	v_mov_b32_e32 v0, s2
	ds_read_b32 v2, v0
	s_cbranch_vccnz .LBB0_1932
	v_readlane_b32 s4, v253, 4
	v_readlane_b32 s5, v253, 5
	s_load_dwordx2 s[2:3], s[4:5], 0x4
	s_mov_b32 s9, 1
	s_waitcnt lgkmcnt(0)
	s_mul_i32 s8, s2, s89
	s_mul_i32 s8, s8, s3
	s_branch .LBB0_1920
